# selected branch: speculative exp with row-sum trigger for the rare reference raise; rowmax chains in FoX, pass A and window as max3 trees
# speedup vs baseline: 1.1152x; 1.0137x over previous
.LBB0_295:
	s_nop 8
	v_max3_f32 v124, v33, v49, v34
	v_max3_f32 v125, v50, v35, v51
	v_max3_f32 v126, v48, v32, v36
	v_max3_f32 v127, v52, v37, v53
	v_max3_f32 v124, v124, v38, v54
	v_max3_f32 v125, v125, v39, v55
	v_max3_f32 v126, v126, v40, v56
	v_max3_f32 v127, v127, v41, v57
	v_max3_f32 v124, v124, v42, v58
	v_max3_f32 v125, v125, v43, v59
	v_max3_f32 v126, v126, v44, v60
	v_max3_f32 v127, v127, v45, v61
	v_max3_f32 v124, v124, v46, v62
	v_max3_f32 v125, v125, v47, v63
	v_max3_f32 v124, v124, v125, v126
	v_max_f32_e32 v124, v124, v127
	ds_bpermute_b32 v125, v113, v124
	s_waitcnt lgkmcnt(0)
	v_max3_f32 v124, v123, v124, v125
	v_sub_f32_e32 v123, v123, v124
	v_exp_f32_e32 v123, v123
	s_nop 0
	v_cmp_eq_f32_e32 vcc, 1.0, v123
	s_cmp_eq_u64 vcc, exec
	s_cbranch_scc1 .LBB0_299
	s_and_saveexec_b64 s[84:85], s[20:21]
	ds_write_b32 v118, v123 offset:32768
	s_or_b64 exec, exec, s[84:85]
	v_add_u32_e32 v125, s96, v98
	ds_read_b128 v[126:129], v125 offset:32864
	ds_read_b128 v[130:133], v125 offset:32832
	ds_read_b128 v[134:137], v125 offset:32800
	ds_read_b128 v[138:141], v125 offset:32768
	s_waitcnt lgkmcnt(3)
	v_pk_mul_f32 v[12:13], v[12:13], v[126:127]
	s_waitcnt lgkmcnt(2)
	v_pk_mul_f32 v[8:9], v[8:9], v[130:131]
	s_waitcnt lgkmcnt(1)
	v_pk_mul_f32 v[4:5], v[4:5], v[134:135]
	v_pk_mul_f32 v[14:15], v[14:15], v[128:129]
	v_pk_mul_f32 v[10:11], v[10:11], v[132:133]
	v_pk_mul_f32 v[6:7], v[6:7], v[136:137]
	s_waitcnt lgkmcnt(0)
	v_pk_mul_f32 v[2:3], v[2:3], v[140:141]
	v_pk_mul_f32 v[0:1], v[0:1], v[138:139]
	v_pk_mul_f32 v[28:29], v[28:29], v[126:127]
	v_pk_mul_f32 v[24:25], v[24:25], v[130:131]
	v_pk_mul_f32 v[20:21], v[20:21], v[134:135]
	v_pk_mul_f32 v[30:31], v[30:31], v[128:129]
	v_pk_mul_f32 v[26:27], v[26:27], v[132:133]
	v_pk_mul_f32 v[22:23], v[22:23], v[136:137]
	v_pk_mul_f32 v[18:19], v[18:19], v[140:141]
	v_pk_mul_f32 v[16:17], v[16:17], v[138:139]

.LBB0_3833:
	s_nop 8
	v_max3_f32 v47, v3, v19, v4
	v_max3_f32 v53, v20, v5, v21
	v_max3_f32 v54, v18, v2, v6
	v_max3_f32 v55, v22, v7, v23
	v_max3_f32 v47, v47, v8, v24
	v_max3_f32 v53, v53, v9, v25
	v_max3_f32 v54, v54, v10, v26
	v_max3_f32 v55, v55, v11, v27
	v_max3_f32 v47, v47, v12, v28
	v_max3_f32 v53, v53, v13, v29
	v_max3_f32 v54, v54, v14, v30
	v_max3_f32 v55, v55, v15, v31
	v_max3_f32 v47, v47, v16, v32
	v_max3_f32 v53, v53, v17, v33
	v_max3_f32 v47, v47, v53, v54
	v_max_f32_e32 v47, v47, v55
	ds_bpermute_b32 v53, v179, v47
	s_add_i32 s10, s10, 1
	s_cmp_ge_u32 s10, s15
	s_cbranch_scc1 .LBB0_3835
	s_and_b32 s13, s11, 0x4000
	v_add_u32_e32 v54, s13, v184
	ds_write_b128 v54, v[38:41]

.Lsb_wd_24:
	s_bfe_u32 s22, s17, 0x40000
	s_cmp_eq_u32 s22, 0
	s_cbranch_scc1 .Lsb_sg_25
	s_lshr_b32 s22, s17, 0
	v_lshrrev_b32_e64 v203, v165, s22
	v_and_b32_e32 v203, 1, v203
	v_cmp_eq_u32_e64 s[10:11], 1, v203
	s_setprio 1
	v_mfma_f32_16x16x32_fp8_fp8 v[66:69], v[2:3], v[144:145], 0
	v_mfma_f32_16x16x32_fp8_fp8 v[70:73], v[6:7], v[144:145], 0
	v_mfma_f32_16x16x32_fp8_fp8 v[74:77], v[10:11], v[144:145], 0
	v_mfma_f32_16x16x32_fp8_fp8 v[78:81], v[14:15], v[144:145], 0
	v_mfma_f32_16x16x32_fp8_fp8 v[66:69], v[4:5], v[146:147], v[66:69]
	v_mfma_f32_16x16x32_fp8_fp8 v[70:73], v[8:9], v[146:147], v[70:73]
	v_mfma_f32_16x16x32_fp8_fp8 v[74:77], v[12:13], v[146:147], v[74:77]
	v_mfma_f32_16x16x32_fp8_fp8 v[78:81], v[16:17], v[146:147], v[78:81]
	s_setprio 0
	v_cndmask_b32_e64 v204, v200, v158, s[10:11]
	s_cmp_eq_u32 s14, s48
	s_nop 1
	s_cbranch_scc1 .Lsb_dg_26
.Lsb_fa_27:
	s_mov_b32 s22, 0x3e38aa3b
	v_fma_f32 v66, v66, s22, -v204
	v_fma_f32 v67, v67, s22, -v204
	v_fma_f32 v68, v68, s22, -v204
	v_fma_f32 v69, v69, s22, -v204
	v_fma_f32 v70, v70, s22, -v204
	v_fma_f32 v71, v71, s22, -v204
	v_fma_f32 v72, v72, s22, -v204
	v_fma_f32 v73, v73, s22, -v204
	v_fma_f32 v74, v74, s22, -v204
	v_fma_f32 v75, v75, s22, -v204
	v_fma_f32 v76, v76, s22, -v204
	v_fma_f32 v77, v77, s22, -v204
	v_fma_f32 v78, v78, s22, -v204
	v_fma_f32 v79, v79, s22, -v204
	v_fma_f32 v80, v80, s22, -v204
	v_fma_f32 v81, v81, s22, -v204
	v_exp_f32_e32 v66, v66
	v_exp_f32_e32 v67, v67
	v_exp_f32_e32 v68, v68
	v_exp_f32_e32 v69, v69
	v_exp_f32_e32 v70, v70
	v_exp_f32_e32 v71, v71
	v_exp_f32_e32 v72, v72
	v_exp_f32_e32 v73, v73
	v_exp_f32_e32 v74, v74
	v_exp_f32_e32 v75, v75
	v_exp_f32_e32 v76, v76
	v_exp_f32_e32 v77, v77
	v_exp_f32_e32 v78, v78
	v_exp_f32_e32 v79, v79
	v_exp_f32_e32 v80, v80
	v_exp_f32_e32 v81, v81
	v_add_f32_e32 v244, v66, v70
	v_add_f32_e32 v245, v67, v71
	v_add_f32_e32 v246, v68, v72
	v_add_f32_e32 v247, v69, v73
	v_add_f32_e32 v248, v74, v78
	v_add_f32_e32 v249, v75, v79
	v_add_f32_e32 v250, v76, v80
	v_add_f32_e32 v251, v77, v81
	v_add_f32_e32 v244, v244, v248
	v_add_f32_e32 v245, v245, v249
	v_add_f32_e32 v246, v246, v250
	v_add_f32_e32 v247, v247, v251
	v_add_f32_e32 v244, v244, v245
	v_add_f32_e32 v246, v246, v247
	v_add_f32_e32 v244, v244, v246
	v_cmp_lt_f32_e32 vcc, 0x43800000, v244
	v_cvt_pk_fp8_f32 v154, v66, v67
	v_cvt_pk_fp8_f32 v155, v70, v71
	v_cvt_pk_fp8_f32 v156, v74, v75
	v_cvt_pk_fp8_f32 v157, v78, v79
	v_cvt_pk_fp8_f32 v154, v68, v69 op_sel:[0,0,1]
	v_cvt_pk_fp8_f32 v155, v72, v73 op_sel:[0,0,1]
	v_cvt_pk_fp8_f32 v156, v76, v77 op_sel:[0,0,1]
	v_cvt_pk_fp8_f32 v157, v80, v81 op_sel:[0,0,1]
	s_cbranch_vccnz .Lsb_sl_28
.Lsb_pv_29:
	v_add_f32_e32 v159, v159, v244
	s_setprio 1
	v_mfma_f32_16x16x32_fp8_fp8 v[102:105], v[18:19], v[154:155], v[102:105]
	v_mfma_f32_16x16x32_fp8_fp8 v[106:109], v[22:23], v[154:155], v[106:109]
	v_mfma_f32_16x16x32_fp8_fp8 v[110:113], v[26:27], v[154:155], v[110:113]
	v_mfma_f32_16x16x32_fp8_fp8 v[114:117], v[30:31], v[154:155], v[114:117]
	v_mfma_f32_16x16x32_fp8_fp8 v[102:105], v[20:21], v[156:157], v[102:105]
	v_mfma_f32_16x16x32_fp8_fp8 v[106:109], v[24:25], v[156:157], v[106:109]
	v_mfma_f32_16x16x32_fp8_fp8 v[110:113], v[28:29], v[156:157], v[110:113]
	v_mfma_f32_16x16x32_fp8_fp8 v[114:117], v[32:33], v[156:157], v[114:117]
	s_setprio 0
	s_branch .Lsb_ce_32
.Lsb_dg_26:
	s_nop 4
	v_sub_u32_e32 v244, v206, v187
	v_cmp_gt_i32_e32 vcc, 0, v244
	v_cmp_gt_i32_e64 s[22:23], 1, v244
	s_nop 0
	v_cndmask_b32_e32 v66, v66, v199, vcc
	v_cndmask_b32_e64 v67, v67, v199, s[22:23]
	v_cmp_gt_i32_e32 vcc, 2, v244
	v_cmp_gt_i32_e64 s[22:23], 3, v244
	s_nop 0
	v_cndmask_b32_e32 v68, v68, v199, vcc
	v_cndmask_b32_e64 v69, v69, v199, s[22:23]
	v_sub_u32_e32 v244, v206, v187
	v_subrev_u32_e32 v244, 16, v244
	v_cmp_gt_i32_e32 vcc, 0, v244
	v_cmp_gt_i32_e64 s[22:23], 1, v244
	s_nop 0
	v_cndmask_b32_e32 v70, v70, v199, vcc
	v_cndmask_b32_e64 v71, v71, v199, s[22:23]
	v_cmp_gt_i32_e32 vcc, 2, v244
	v_cmp_gt_i32_e64 s[22:23], 3, v244
	s_nop 0
	v_cndmask_b32_e32 v72, v72, v199, vcc
	v_cndmask_b32_e64 v73, v73, v199, s[22:23]
	v_sub_u32_e32 v244, v206, v187
	v_subrev_u32_e32 v244, 32, v244
	v_cmp_gt_i32_e32 vcc, 0, v244
	v_cmp_gt_i32_e64 s[22:23], 1, v244
	s_nop 0
	v_cndmask_b32_e32 v74, v74, v199, vcc
	v_cndmask_b32_e64 v75, v75, v199, s[22:23]
	v_cmp_gt_i32_e32 vcc, 2, v244
	v_cmp_gt_i32_e64 s[22:23], 3, v244
	s_nop 0
	v_cndmask_b32_e32 v76, v76, v199, vcc
	v_cndmask_b32_e64 v77, v77, v199, s[22:23]
	v_sub_u32_e32 v244, v206, v187
	v_subrev_u32_e32 v244, 48, v244
	v_cmp_gt_i32_e32 vcc, 0, v244
	v_cmp_gt_i32_e64 s[22:23], 1, v244
	s_nop 0
	v_cndmask_b32_e32 v78, v78, v199, vcc
	v_cndmask_b32_e64 v79, v79, v199, s[22:23]
	v_cmp_gt_i32_e32 vcc, 2, v244
	v_cmp_gt_i32_e64 s[22:23], 3, v244
	s_nop 0
	v_cndmask_b32_e32 v80, v80, v199, vcc
	v_cndmask_b32_e64 v81, v81, v199, s[22:23]
	s_branch .Lsb_fa_27
.Lsb_sl_28:
	s_setprio 1
	v_mfma_f32_16x16x32_fp8_fp8 v[66:69], v[2:3], v[144:145], 0
	v_mfma_f32_16x16x32_fp8_fp8 v[70:73], v[6:7], v[144:145], 0
	v_mfma_f32_16x16x32_fp8_fp8 v[74:77], v[10:11], v[144:145], 0
	v_mfma_f32_16x16x32_fp8_fp8 v[78:81], v[14:15], v[144:145], 0
	v_mfma_f32_16x16x32_fp8_fp8 v[66:69], v[4:5], v[146:147], v[66:69]
	v_mfma_f32_16x16x32_fp8_fp8 v[70:73], v[8:9], v[146:147], v[70:73]
	v_mfma_f32_16x16x32_fp8_fp8 v[74:77], v[12:13], v[146:147], v[74:77]
	v_mfma_f32_16x16x32_fp8_fp8 v[78:81], v[16:17], v[146:147], v[78:81]
	s_setprio 0
	s_cmp_lg_u32 s14, s48
	s_nop 7
	s_cbranch_scc1 .Lsb_sn_31
	v_sub_u32_e32 v244, v206, v187
	v_cmp_gt_i32_e32 vcc, 0, v244
	v_cmp_gt_i32_e64 s[22:23], 1, v244
	s_nop 0
	v_cndmask_b32_e32 v66, v66, v199, vcc
	v_cndmask_b32_e64 v67, v67, v199, s[22:23]
	v_cmp_gt_i32_e32 vcc, 2, v244
	v_cmp_gt_i32_e64 s[22:23], 3, v244
	s_nop 0
	v_cndmask_b32_e32 v68, v68, v199, vcc
	v_cndmask_b32_e64 v69, v69, v199, s[22:23]
	v_sub_u32_e32 v244, v206, v187
	v_subrev_u32_e32 v244, 16, v244
	v_cmp_gt_i32_e32 vcc, 0, v244
	v_cmp_gt_i32_e64 s[22:23], 1, v244
	s_nop 0
	v_cndmask_b32_e32 v70, v70, v199, vcc
	v_cndmask_b32_e64 v71, v71, v199, s[22:23]
	v_cmp_gt_i32_e32 vcc, 2, v244
	v_cmp_gt_i32_e64 s[22:23], 3, v244
	s_nop 0
	v_cndmask_b32_e32 v72, v72, v199, vcc
	v_cndmask_b32_e64 v73, v73, v199, s[22:23]
	v_sub_u32_e32 v244, v206, v187
	v_subrev_u32_e32 v244, 32, v244
	v_cmp_gt_i32_e32 vcc, 0, v244
	v_cmp_gt_i32_e64 s[22:23], 1, v244
	s_nop 0
	v_cndmask_b32_e32 v74, v74, v199, vcc
	v_cndmask_b32_e64 v75, v75, v199, s[22:23]
	v_cmp_gt_i32_e32 vcc, 2, v244
	v_cmp_gt_i32_e64 s[22:23], 3, v244
	s_nop 0
	v_cndmask_b32_e32 v76, v76, v199, vcc
	v_cndmask_b32_e64 v77, v77, v199, s[22:23]
	v_sub_u32_e32 v244, v206, v187
	v_subrev_u32_e32 v244, 48, v244
	v_cmp_gt_i32_e32 vcc, 0, v244
	v_cmp_gt_i32_e64 s[22:23], 1, v244
	s_nop 0
	v_cndmask_b32_e32 v78, v78, v199, vcc
	v_cndmask_b32_e64 v79, v79, v199, s[22:23]
	v_cmp_gt_i32_e32 vcc, 2, v244
	v_cmp_gt_i32_e64 s[22:23], 3, v244
	s_nop 0
	v_cndmask_b32_e32 v80, v80, v199, vcc
	v_cndmask_b32_e64 v81, v81, v199, s[22:23]
.Lsb_sn_31:
	v_max3_f32 v202, v66, v67, v68
	v_max3_f32 v203, v69, v70, v71
	v_max3_f32 v202, v202, v72, v73
	v_max3_f32 v203, v203, v74, v75
	v_max3_f32 v202, v202, v76, v77
	v_max3_f32 v203, v203, v78, v79
	v_max3_f32 v202, v202, v80, v81
	v_max_f32_e32 v202, v202, v203
	v_mul_f32_e32 v202, 0x3e38aa3b, v202
	v_cndmask_b32_e64 v202, v199, v202, s[10:11]
	ds_bpermute_b32 v203, v197, v202
	s_waitcnt lgkmcnt(0)
	v_max_f32_e32 v203, v202, v203
	ds_bpermute_b32 v133, v198, v203
	s_waitcnt lgkmcnt(0)
	v_max_f32_e32 v203, v203, v133
	v_max_f32_e32 v203, v158, v203
	v_sub_f32_e32 v133, v158, v203
	v_exp_f32_e32 v133, v133
	v_mov_b32_e32 v158, v203
	s_nop 0
	v_mul_f32_e32 v159, v159, v133
	v_mul_f32_e32 v102, v102, v133
	v_mul_f32_e32 v103, v103, v133
	v_mul_f32_e32 v104, v104, v133
	v_mul_f32_e32 v105, v105, v133
	v_mul_f32_e32 v106, v106, v133
	v_mul_f32_e32 v107, v107, v133
	v_mul_f32_e32 v108, v108, v133
	v_mul_f32_e32 v109, v109, v133
	v_mul_f32_e32 v110, v110, v133
	v_mul_f32_e32 v111, v111, v133
	v_mul_f32_e32 v112, v112, v133
	v_mul_f32_e32 v113, v113, v133
	v_mul_f32_e32 v114, v114, v133
	v_mul_f32_e32 v115, v115, v133
	v_mul_f32_e32 v116, v116, v133
	v_mul_f32_e32 v117, v117, v133
	v_cndmask_b32_e64 v204, v200, v158, s[10:11]
	s_mov_b32 s22, 0x3e38aa3b
	v_fma_f32 v66, v66, s22, -v204
	v_fma_f32 v67, v67, s22, -v204
	v_fma_f32 v68, v68, s22, -v204
	v_fma_f32 v69, v69, s22, -v204
	v_fma_f32 v70, v70, s22, -v204
	v_fma_f32 v71, v71, s22, -v204
	v_fma_f32 v72, v72, s22, -v204
	v_fma_f32 v73, v73, s22, -v204
	v_fma_f32 v74, v74, s22, -v204
	v_fma_f32 v75, v75, s22, -v204
	v_fma_f32 v76, v76, s22, -v204
	v_fma_f32 v77, v77, s22, -v204
	v_fma_f32 v78, v78, s22, -v204
	v_fma_f32 v79, v79, s22, -v204
	v_fma_f32 v80, v80, s22, -v204
	v_fma_f32 v81, v81, s22, -v204
	v_exp_f32_e32 v66, v66
	v_exp_f32_e32 v67, v67
	v_exp_f32_e32 v68, v68
	v_exp_f32_e32 v69, v69
	v_exp_f32_e32 v70, v70
	v_exp_f32_e32 v71, v71
	v_exp_f32_e32 v72, v72
	v_exp_f32_e32 v73, v73
	v_exp_f32_e32 v74, v74
	v_exp_f32_e32 v75, v75
	v_exp_f32_e32 v76, v76
	v_exp_f32_e32 v77, v77
	v_exp_f32_e32 v78, v78
	v_exp_f32_e32 v79, v79
	v_exp_f32_e32 v80, v80
	v_exp_f32_e32 v81, v81
	v_add_f32_e32 v244, v66, v70
	v_add_f32_e32 v245, v67, v71
	v_add_f32_e32 v246, v68, v72
	v_add_f32_e32 v247, v69, v73
	v_add_f32_e32 v248, v74, v78
	v_add_f32_e32 v249, v75, v79
	v_add_f32_e32 v250, v76, v80
	v_add_f32_e32 v251, v77, v81
	v_add_f32_e32 v244, v244, v248
	v_add_f32_e32 v245, v245, v249
	v_add_f32_e32 v246, v246, v250
	v_add_f32_e32 v247, v247, v251
	v_add_f32_e32 v244, v244, v245
	v_add_f32_e32 v246, v246, v247
	v_add_f32_e32 v244, v244, v246
	v_cvt_pk_fp8_f32 v154, v66, v67
	v_cvt_pk_fp8_f32 v155, v70, v71
	v_cvt_pk_fp8_f32 v156, v74, v75
	v_cvt_pk_fp8_f32 v157, v78, v79
	v_cvt_pk_fp8_f32 v154, v68, v69 op_sel:[0,0,1]
	v_cvt_pk_fp8_f32 v155, v72, v73 op_sel:[0,0,1]
	v_cvt_pk_fp8_f32 v156, v76, v77 op_sel:[0,0,1]
	v_cvt_pk_fp8_f32 v157, v80, v81 op_sel:[0,0,1]
	s_nop 0
	s_branch .Lsb_pv_29
.Lsb_ce_32:
.Lsb_sg_25:
	s_bfe_u32 s22, s17, 0x40004
	s_cmp_eq_u32 s22, 0
	s_cbranch_scc1 .Lsb_sg_33
	s_lshr_b32 s22, s17, 4
	v_lshrrev_b32_e64 v203, v165, s22
	v_and_b32_e32 v203, 1, v203
	v_cmp_eq_u32_e64 s[10:11], 1, v203
	s_setprio 1
	v_mfma_f32_16x16x32_fp8_fp8 v[66:69], v[2:3], v[150:151], 0
	v_mfma_f32_16x16x32_fp8_fp8 v[70:73], v[6:7], v[150:151], 0
	v_mfma_f32_16x16x32_fp8_fp8 v[74:77], v[10:11], v[150:151], 0
	v_mfma_f32_16x16x32_fp8_fp8 v[78:81], v[14:15], v[150:151], 0
	v_mfma_f32_16x16x32_fp8_fp8 v[66:69], v[4:5], v[152:153], v[66:69]
	v_mfma_f32_16x16x32_fp8_fp8 v[70:73], v[8:9], v[152:153], v[70:73]
	v_mfma_f32_16x16x32_fp8_fp8 v[74:77], v[12:13], v[152:153], v[74:77]
	v_mfma_f32_16x16x32_fp8_fp8 v[78:81], v[16:17], v[152:153], v[78:81]
	s_setprio 0
	v_cndmask_b32_e64 v204, v200, v162, s[10:11]
	s_cmp_eq_u32 s14, s48
	s_nop 1
	s_cbranch_scc1 .Lsb_dg_34

.Lsb_pv_37:
	v_add_f32_e32 v163, v163, v244
	s_setprio 1
	v_mfma_f32_16x16x32_fp8_fp8 v[118:121], v[18:19], v[154:155], v[118:121]
	v_mfma_f32_16x16x32_fp8_fp8 v[122:125], v[22:23], v[154:155], v[122:125]
	v_mfma_f32_16x16x32_fp8_fp8 v[136:139], v[26:27], v[154:155], v[136:139]
	v_mfma_f32_16x16x32_fp8_fp8 v[140:143], v[30:31], v[154:155], v[140:143]
	v_mfma_f32_16x16x32_fp8_fp8 v[118:121], v[20:21], v[156:157], v[118:121]
	v_mfma_f32_16x16x32_fp8_fp8 v[122:125], v[24:25], v[156:157], v[122:125]
	v_mfma_f32_16x16x32_fp8_fp8 v[136:139], v[28:29], v[156:157], v[136:139]
	v_mfma_f32_16x16x32_fp8_fp8 v[140:143], v[32:33], v[156:157], v[140:143]
	s_setprio 0
	s_branch .Lsb_ce_40
.Lsb_dg_34:
	s_nop 4
	v_sub_u32_e32 v244, v206, v187
	v_subrev_u32_e32 v244, -4, v244
	v_cmp_gt_i32_e32 vcc, 0, v244
	v_cmp_gt_i32_e64 s[22:23], 1, v244
	s_nop 0
	v_cndmask_b32_e32 v66, v66, v199, vcc
	v_cndmask_b32_e64 v67, v67, v199, s[22:23]
	v_cmp_gt_i32_e32 vcc, 2, v244
	v_cmp_gt_i32_e64 s[22:23], 3, v244
	s_nop 0
	v_cndmask_b32_e32 v68, v68, v199, vcc
	v_cndmask_b32_e64 v69, v69, v199, s[22:23]
	v_sub_u32_e32 v244, v206, v187
	v_subrev_u32_e32 v244, 12, v244
	v_cmp_gt_i32_e32 vcc, 0, v244
	v_cmp_gt_i32_e64 s[22:23], 1, v244
	s_nop 0
	v_cndmask_b32_e32 v70, v70, v199, vcc
	v_cndmask_b32_e64 v71, v71, v199, s[22:23]
	v_cmp_gt_i32_e32 vcc, 2, v244
	v_cmp_gt_i32_e64 s[22:23], 3, v244
	s_nop 0
	v_cndmask_b32_e32 v72, v72, v199, vcc
	v_cndmask_b32_e64 v73, v73, v199, s[22:23]
	v_sub_u32_e32 v244, v206, v187
	v_subrev_u32_e32 v244, 28, v244
	v_cmp_gt_i32_e32 vcc, 0, v244
	v_cmp_gt_i32_e64 s[22:23], 1, v244
	s_nop 0
	v_cndmask_b32_e32 v74, v74, v199, vcc
	v_cndmask_b32_e64 v75, v75, v199, s[22:23]
	v_cmp_gt_i32_e32 vcc, 2, v244
	v_cmp_gt_i32_e64 s[22:23], 3, v244
	s_nop 0
	v_cndmask_b32_e32 v76, v76, v199, vcc
	v_cndmask_b32_e64 v77, v77, v199, s[22:23]
	v_sub_u32_e32 v244, v206, v187
	v_subrev_u32_e32 v244, 44, v244
	v_cmp_gt_i32_e32 vcc, 0, v244
	v_cmp_gt_i32_e64 s[22:23], 1, v244
	s_nop 0
	v_cndmask_b32_e32 v78, v78, v199, vcc
	v_cndmask_b32_e64 v79, v79, v199, s[22:23]
	v_cmp_gt_i32_e32 vcc, 2, v244
	v_cmp_gt_i32_e64 s[22:23], 3, v244
	s_nop 0
	v_cndmask_b32_e32 v80, v80, v199, vcc
	v_cndmask_b32_e64 v81, v81, v199, s[22:23]
	s_branch .Lsb_fa_35
.Lsb_sl_36:
	s_setprio 1
	v_mfma_f32_16x16x32_fp8_fp8 v[66:69], v[2:3], v[150:151], 0
	v_mfma_f32_16x16x32_fp8_fp8 v[70:73], v[6:7], v[150:151], 0
	v_mfma_f32_16x16x32_fp8_fp8 v[74:77], v[10:11], v[150:151], 0
	v_mfma_f32_16x16x32_fp8_fp8 v[78:81], v[14:15], v[150:151], 0
	v_mfma_f32_16x16x32_fp8_fp8 v[66:69], v[4:5], v[152:153], v[66:69]
	v_mfma_f32_16x16x32_fp8_fp8 v[70:73], v[8:9], v[152:153], v[70:73]
	v_mfma_f32_16x16x32_fp8_fp8 v[74:77], v[12:13], v[152:153], v[74:77]
	v_mfma_f32_16x16x32_fp8_fp8 v[78:81], v[16:17], v[152:153], v[78:81]
	s_setprio 0
	s_cmp_lg_u32 s14, s48
	s_nop 7
	s_cbranch_scc1 .Lsb_sn_39
	v_sub_u32_e32 v244, v206, v187
	v_subrev_u32_e32 v244, -4, v244
	v_cmp_gt_i32_e32 vcc, 0, v244
	v_cmp_gt_i32_e64 s[22:23], 1, v244
	s_nop 0
	v_cndmask_b32_e32 v66, v66, v199, vcc
	v_cndmask_b32_e64 v67, v67, v199, s[22:23]
	v_cmp_gt_i32_e32 vcc, 2, v244
	v_cmp_gt_i32_e64 s[22:23], 3, v244
	s_nop 0
	v_cndmask_b32_e32 v68, v68, v199, vcc
	v_cndmask_b32_e64 v69, v69, v199, s[22:23]
	v_sub_u32_e32 v244, v206, v187
	v_subrev_u32_e32 v244, 12, v244
	v_cmp_gt_i32_e32 vcc, 0, v244
	v_cmp_gt_i32_e64 s[22:23], 1, v244
	s_nop 0
	v_cndmask_b32_e32 v70, v70, v199, vcc
	v_cndmask_b32_e64 v71, v71, v199, s[22:23]
	v_cmp_gt_i32_e32 vcc, 2, v244
	v_cmp_gt_i32_e64 s[22:23], 3, v244
	s_nop 0
	v_cndmask_b32_e32 v72, v72, v199, vcc
	v_cndmask_b32_e64 v73, v73, v199, s[22:23]
	v_sub_u32_e32 v244, v206, v187
	v_subrev_u32_e32 v244, 28, v244
	v_cmp_gt_i32_e32 vcc, 0, v244
	v_cmp_gt_i32_e64 s[22:23], 1, v244
	s_nop 0
	v_cndmask_b32_e32 v74, v74, v199, vcc
	v_cndmask_b32_e64 v75, v75, v199, s[22:23]
	v_cmp_gt_i32_e32 vcc, 2, v244
	v_cmp_gt_i32_e64 s[22:23], 3, v244
	s_nop 0
	v_cndmask_b32_e32 v76, v76, v199, vcc
	v_cndmask_b32_e64 v77, v77, v199, s[22:23]
	v_sub_u32_e32 v244, v206, v187
	v_subrev_u32_e32 v244, 44, v244
	v_cmp_gt_i32_e32 vcc, 0, v244
	v_cmp_gt_i32_e64 s[22:23], 1, v244
	s_nop 0
	v_cndmask_b32_e32 v78, v78, v199, vcc
	v_cndmask_b32_e64 v79, v79, v199, s[22:23]
	v_cmp_gt_i32_e32 vcc, 2, v244
	v_cmp_gt_i32_e64 s[22:23], 3, v244
	s_nop 0
	v_cndmask_b32_e32 v80, v80, v199, vcc
	v_cndmask_b32_e64 v81, v81, v199, s[22:23]
.Lsb_sn_39:
	v_max3_f32 v202, v66, v67, v68
	v_max3_f32 v203, v69, v70, v71
	v_max3_f32 v202, v202, v72, v73
	v_max3_f32 v203, v203, v74, v75
	v_max3_f32 v202, v202, v76, v77
	v_max3_f32 v203, v203, v78, v79
	v_max3_f32 v202, v202, v80, v81
	v_max_f32_e32 v202, v202, v203
	v_mul_f32_e32 v202, 0x3e38aa3b, v202
	v_cndmask_b32_e64 v202, v199, v202, s[10:11]
	ds_bpermute_b32 v203, v197, v202
	s_waitcnt lgkmcnt(0)
	v_max_f32_e32 v203, v202, v203
	ds_bpermute_b32 v133, v198, v203
	s_waitcnt lgkmcnt(0)
	v_max_f32_e32 v203, v203, v133
	v_max_f32_e32 v203, v162, v203
	v_sub_f32_e32 v133, v162, v203
	v_exp_f32_e32 v133, v133
	v_mov_b32_e32 v162, v203
	s_nop 0
	v_mul_f32_e32 v163, v163, v133
	v_mul_f32_e32 v118, v118, v133
	v_mul_f32_e32 v119, v119, v133
	v_mul_f32_e32 v120, v120, v133
	v_mul_f32_e32 v121, v121, v133
	v_mul_f32_e32 v122, v122, v133
	v_mul_f32_e32 v123, v123, v133
	v_mul_f32_e32 v124, v124, v133
	v_mul_f32_e32 v125, v125, v133
	v_mul_f32_e32 v136, v136, v133
	v_mul_f32_e32 v137, v137, v133
	v_mul_f32_e32 v138, v138, v133
	v_mul_f32_e32 v139, v139, v133
	v_mul_f32_e32 v140, v140, v133
	v_mul_f32_e32 v141, v141, v133
	v_mul_f32_e32 v142, v142, v133
	v_mul_f32_e32 v143, v143, v133
	v_cndmask_b32_e64 v204, v200, v162, s[10:11]
	s_mov_b32 s22, 0x3e38aa3b
	v_fma_f32 v66, v66, s22, -v204
	v_fma_f32 v67, v67, s22, -v204
	v_fma_f32 v68, v68, s22, -v204
	v_fma_f32 v69, v69, s22, -v204
	v_fma_f32 v70, v70, s22, -v204
	v_fma_f32 v71, v71, s22, -v204
	v_fma_f32 v72, v72, s22, -v204
	v_fma_f32 v73, v73, s22, -v204
	v_fma_f32 v74, v74, s22, -v204
	v_fma_f32 v75, v75, s22, -v204
	v_fma_f32 v76, v76, s22, -v204
	v_fma_f32 v77, v77, s22, -v204
	v_fma_f32 v78, v78, s22, -v204
	v_fma_f32 v79, v79, s22, -v204
	v_fma_f32 v80, v80, s22, -v204
	v_fma_f32 v81, v81, s22, -v204
	v_exp_f32_e32 v66, v66
	v_exp_f32_e32 v67, v67
	v_exp_f32_e32 v68, v68
	v_exp_f32_e32 v69, v69
	v_exp_f32_e32 v70, v70
	v_exp_f32_e32 v71, v71
	v_exp_f32_e32 v72, v72
	v_exp_f32_e32 v73, v73
	v_exp_f32_e32 v74, v74
	v_exp_f32_e32 v75, v75
	v_exp_f32_e32 v76, v76
	v_exp_f32_e32 v77, v77
	v_exp_f32_e32 v78, v78
	v_exp_f32_e32 v79, v79
	v_exp_f32_e32 v80, v80
	v_exp_f32_e32 v81, v81
	v_add_f32_e32 v244, v66, v70
	v_add_f32_e32 v245, v67, v71
	v_add_f32_e32 v246, v68, v72
	v_add_f32_e32 v247, v69, v73
	v_add_f32_e32 v248, v74, v78
	v_add_f32_e32 v249, v75, v79
	v_add_f32_e32 v250, v76, v80
	v_add_f32_e32 v251, v77, v81
	v_add_f32_e32 v244, v244, v248
	v_add_f32_e32 v245, v245, v249
	v_add_f32_e32 v246, v246, v250
	v_add_f32_e32 v247, v247, v251
	v_add_f32_e32 v244, v244, v245
	v_add_f32_e32 v246, v246, v247
	v_add_f32_e32 v244, v244, v246
	v_cvt_pk_fp8_f32 v154, v66, v67
	v_cvt_pk_fp8_f32 v155, v70, v71
	v_cvt_pk_fp8_f32 v156, v74, v75
	v_cvt_pk_fp8_f32 v157, v78, v79
	v_cvt_pk_fp8_f32 v154, v68, v69 op_sel:[0,0,1]
	v_cvt_pk_fp8_f32 v155, v72, v73 op_sel:[0,0,1]
	v_cvt_pk_fp8_f32 v156, v76, v77 op_sel:[0,0,1]
	v_cvt_pk_fp8_f32 v157, v80, v81 op_sel:[0,0,1]
	s_nop 0
	s_branch .Lsb_pv_37
.Lsb_ce_40:
.Lsb_sg_33:
	s_mov_b32 s14, s15
	s_mov_b32 s15, s16
	s_mov_b32 s17, s18
	s_mov_b32 s18, s19
	s_mov_b32 s24, s25

.Lsb_wd_49:
	s_bfe_u32 s22, s17, 0x40000
	s_cmp_eq_u32 s22, 0
	s_cbranch_scc1 .Lsb_sg_50
	s_lshr_b32 s22, s17, 0
	v_lshrrev_b32_e64 v203, v165, s22
	v_and_b32_e32 v203, 1, v203
	v_cmp_eq_u32_e64 s[10:11], 1, v203
	s_setprio 1
	v_mfma_f32_16x16x32_fp8_fp8 v[66:69], v[34:35], v[144:145], 0
	v_mfma_f32_16x16x32_fp8_fp8 v[70:73], v[38:39], v[144:145], 0
	v_mfma_f32_16x16x32_fp8_fp8 v[74:77], v[42:43], v[144:145], 0
	v_mfma_f32_16x16x32_fp8_fp8 v[78:81], v[46:47], v[144:145], 0
	v_mfma_f32_16x16x32_fp8_fp8 v[66:69], v[36:37], v[146:147], v[66:69]
	v_mfma_f32_16x16x32_fp8_fp8 v[70:73], v[40:41], v[146:147], v[70:73]
	v_mfma_f32_16x16x32_fp8_fp8 v[74:77], v[44:45], v[146:147], v[74:77]
	v_mfma_f32_16x16x32_fp8_fp8 v[78:81], v[48:49], v[146:147], v[78:81]
	s_setprio 0
	v_cndmask_b32_e64 v204, v200, v158, s[10:11]
	s_cmp_eq_u32 s14, s48
	s_nop 1
	s_cbranch_scc1 .Lsb_dg_51

.Lsb_pv_54:
	v_add_f32_e32 v159, v159, v244
	s_setprio 1
	v_mfma_f32_16x16x32_fp8_fp8 v[102:105], v[50:51], v[154:155], v[102:105]
	v_mfma_f32_16x16x32_fp8_fp8 v[106:109], v[54:55], v[154:155], v[106:109]
	v_mfma_f32_16x16x32_fp8_fp8 v[110:113], v[58:59], v[154:155], v[110:113]
	v_mfma_f32_16x16x32_fp8_fp8 v[114:117], v[62:63], v[154:155], v[114:117]
	v_mfma_f32_16x16x32_fp8_fp8 v[102:105], v[52:53], v[156:157], v[102:105]
	v_mfma_f32_16x16x32_fp8_fp8 v[106:109], v[56:57], v[156:157], v[106:109]
	v_mfma_f32_16x16x32_fp8_fp8 v[110:113], v[60:61], v[156:157], v[110:113]
	v_mfma_f32_16x16x32_fp8_fp8 v[114:117], v[64:65], v[156:157], v[114:117]
	s_setprio 0
	s_branch .Lsb_ce_57

.Lsb_sl_53:
	s_setprio 1
	v_mfma_f32_16x16x32_fp8_fp8 v[66:69], v[34:35], v[144:145], 0
	v_mfma_f32_16x16x32_fp8_fp8 v[70:73], v[38:39], v[144:145], 0
	v_mfma_f32_16x16x32_fp8_fp8 v[74:77], v[42:43], v[144:145], 0
	v_mfma_f32_16x16x32_fp8_fp8 v[78:81], v[46:47], v[144:145], 0
	v_mfma_f32_16x16x32_fp8_fp8 v[66:69], v[36:37], v[146:147], v[66:69]
	v_mfma_f32_16x16x32_fp8_fp8 v[70:73], v[40:41], v[146:147], v[70:73]
	v_mfma_f32_16x16x32_fp8_fp8 v[74:77], v[44:45], v[146:147], v[74:77]
	v_mfma_f32_16x16x32_fp8_fp8 v[78:81], v[48:49], v[146:147], v[78:81]
	s_setprio 0
	s_cmp_lg_u32 s14, s48
	s_nop 7
	s_cbranch_scc1 .Lsb_sn_56
	v_sub_u32_e32 v244, v206, v187
	v_cmp_gt_i32_e32 vcc, 0, v244
	v_cmp_gt_i32_e64 s[22:23], 1, v244
	s_nop 0
	v_cndmask_b32_e32 v66, v66, v199, vcc
	v_cndmask_b32_e64 v67, v67, v199, s[22:23]
	v_cmp_gt_i32_e32 vcc, 2, v244
	v_cmp_gt_i32_e64 s[22:23], 3, v244
	s_nop 0
	v_cndmask_b32_e32 v68, v68, v199, vcc
	v_cndmask_b32_e64 v69, v69, v199, s[22:23]
	v_sub_u32_e32 v244, v206, v187
	v_subrev_u32_e32 v244, 16, v244
	v_cmp_gt_i32_e32 vcc, 0, v244
	v_cmp_gt_i32_e64 s[22:23], 1, v244
	s_nop 0
	v_cndmask_b32_e32 v70, v70, v199, vcc
	v_cndmask_b32_e64 v71, v71, v199, s[22:23]
	v_cmp_gt_i32_e32 vcc, 2, v244
	v_cmp_gt_i32_e64 s[22:23], 3, v244
	s_nop 0
	v_cndmask_b32_e32 v72, v72, v199, vcc
	v_cndmask_b32_e64 v73, v73, v199, s[22:23]
	v_sub_u32_e32 v244, v206, v187
	v_subrev_u32_e32 v244, 32, v244
	v_cmp_gt_i32_e32 vcc, 0, v244
	v_cmp_gt_i32_e64 s[22:23], 1, v244
	s_nop 0
	v_cndmask_b32_e32 v74, v74, v199, vcc
	v_cndmask_b32_e64 v75, v75, v199, s[22:23]
	v_cmp_gt_i32_e32 vcc, 2, v244
	v_cmp_gt_i32_e64 s[22:23], 3, v244
	s_nop 0
	v_cndmask_b32_e32 v76, v76, v199, vcc
	v_cndmask_b32_e64 v77, v77, v199, s[22:23]
	v_sub_u32_e32 v244, v206, v187
	v_subrev_u32_e32 v244, 48, v244
	v_cmp_gt_i32_e32 vcc, 0, v244
	v_cmp_gt_i32_e64 s[22:23], 1, v244
	s_nop 0
	v_cndmask_b32_e32 v78, v78, v199, vcc
	v_cndmask_b32_e64 v79, v79, v199, s[22:23]
	v_cmp_gt_i32_e32 vcc, 2, v244
	v_cmp_gt_i32_e64 s[22:23], 3, v244
	s_nop 0
	v_cndmask_b32_e32 v80, v80, v199, vcc
	v_cndmask_b32_e64 v81, v81, v199, s[22:23]

.Lsb_ce_57:
.Lsb_sg_50:
	s_bfe_u32 s22, s17, 0x40004
	s_cmp_eq_u32 s22, 0
	s_cbranch_scc1 .Lsb_sg_58
	s_lshr_b32 s22, s17, 4
	v_lshrrev_b32_e64 v203, v165, s22
	v_and_b32_e32 v203, 1, v203
	v_cmp_eq_u32_e64 s[10:11], 1, v203
	s_setprio 1
	v_mfma_f32_16x16x32_fp8_fp8 v[66:69], v[34:35], v[150:151], 0
	v_mfma_f32_16x16x32_fp8_fp8 v[70:73], v[38:39], v[150:151], 0
	v_mfma_f32_16x16x32_fp8_fp8 v[74:77], v[42:43], v[150:151], 0
	v_mfma_f32_16x16x32_fp8_fp8 v[78:81], v[46:47], v[150:151], 0
	v_mfma_f32_16x16x32_fp8_fp8 v[66:69], v[36:37], v[152:153], v[66:69]
	v_mfma_f32_16x16x32_fp8_fp8 v[70:73], v[40:41], v[152:153], v[70:73]
	v_mfma_f32_16x16x32_fp8_fp8 v[74:77], v[44:45], v[152:153], v[74:77]
	v_mfma_f32_16x16x32_fp8_fp8 v[78:81], v[48:49], v[152:153], v[78:81]
	s_setprio 0
	v_cndmask_b32_e64 v204, v200, v162, s[10:11]
	s_cmp_eq_u32 s14, s48
	s_nop 1
	s_cbranch_scc1 .Lsb_dg_59

.Lsb_pv_62:
	v_add_f32_e32 v163, v163, v244
	s_setprio 1
	v_mfma_f32_16x16x32_fp8_fp8 v[118:121], v[50:51], v[154:155], v[118:121]
	v_mfma_f32_16x16x32_fp8_fp8 v[122:125], v[54:55], v[154:155], v[122:125]
	v_mfma_f32_16x16x32_fp8_fp8 v[136:139], v[58:59], v[154:155], v[136:139]
	v_mfma_f32_16x16x32_fp8_fp8 v[140:143], v[62:63], v[154:155], v[140:143]
	v_mfma_f32_16x16x32_fp8_fp8 v[118:121], v[52:53], v[156:157], v[118:121]
	v_mfma_f32_16x16x32_fp8_fp8 v[122:125], v[56:57], v[156:157], v[122:125]
	v_mfma_f32_16x16x32_fp8_fp8 v[136:139], v[60:61], v[156:157], v[136:139]
	v_mfma_f32_16x16x32_fp8_fp8 v[140:143], v[64:65], v[156:157], v[140:143]
	s_setprio 0
	s_branch .Lsb_ce_65

.Lsb_sl_61:
	s_setprio 1
	v_mfma_f32_16x16x32_fp8_fp8 v[66:69], v[34:35], v[150:151], 0
	v_mfma_f32_16x16x32_fp8_fp8 v[70:73], v[38:39], v[150:151], 0
	v_mfma_f32_16x16x32_fp8_fp8 v[74:77], v[42:43], v[150:151], 0
	v_mfma_f32_16x16x32_fp8_fp8 v[78:81], v[46:47], v[150:151], 0
	v_mfma_f32_16x16x32_fp8_fp8 v[66:69], v[36:37], v[152:153], v[66:69]
	v_mfma_f32_16x16x32_fp8_fp8 v[70:73], v[40:41], v[152:153], v[70:73]
	v_mfma_f32_16x16x32_fp8_fp8 v[74:77], v[44:45], v[152:153], v[74:77]
	v_mfma_f32_16x16x32_fp8_fp8 v[78:81], v[48:49], v[152:153], v[78:81]
	s_setprio 0
	s_cmp_lg_u32 s14, s48
	s_nop 7
	s_cbranch_scc1 .Lsb_sn_64
	v_sub_u32_e32 v244, v206, v187
	v_subrev_u32_e32 v244, -4, v244
	v_cmp_gt_i32_e32 vcc, 0, v244
	v_cmp_gt_i32_e64 s[22:23], 1, v244
	s_nop 0
	v_cndmask_b32_e32 v66, v66, v199, vcc
	v_cndmask_b32_e64 v67, v67, v199, s[22:23]
	v_cmp_gt_i32_e32 vcc, 2, v244
	v_cmp_gt_i32_e64 s[22:23], 3, v244
	s_nop 0
	v_cndmask_b32_e32 v68, v68, v199, vcc
	v_cndmask_b32_e64 v69, v69, v199, s[22:23]
	v_sub_u32_e32 v244, v206, v187
	v_subrev_u32_e32 v244, 12, v244
	v_cmp_gt_i32_e32 vcc, 0, v244
	v_cmp_gt_i32_e64 s[22:23], 1, v244
	s_nop 0
	v_cndmask_b32_e32 v70, v70, v199, vcc
	v_cndmask_b32_e64 v71, v71, v199, s[22:23]
	v_cmp_gt_i32_e32 vcc, 2, v244
	v_cmp_gt_i32_e64 s[22:23], 3, v244
	s_nop 0
	v_cndmask_b32_e32 v72, v72, v199, vcc
	v_cndmask_b32_e64 v73, v73, v199, s[22:23]
	v_sub_u32_e32 v244, v206, v187
	v_subrev_u32_e32 v244, 28, v244
	v_cmp_gt_i32_e32 vcc, 0, v244
	v_cmp_gt_i32_e64 s[22:23], 1, v244
	s_nop 0
	v_cndmask_b32_e32 v74, v74, v199, vcc
	v_cndmask_b32_e64 v75, v75, v199, s[22:23]
	v_cmp_gt_i32_e32 vcc, 2, v244
	v_cmp_gt_i32_e64 s[22:23], 3, v244
	s_nop 0
	v_cndmask_b32_e32 v76, v76, v199, vcc
	v_cndmask_b32_e64 v77, v77, v199, s[22:23]
	v_sub_u32_e32 v244, v206, v187
	v_subrev_u32_e32 v244, 44, v244
	v_cmp_gt_i32_e32 vcc, 0, v244
	v_cmp_gt_i32_e64 s[22:23], 1, v244
	s_nop 0
	v_cndmask_b32_e32 v78, v78, v199, vcc
	v_cndmask_b32_e64 v79, v79, v199, s[22:23]
	v_cmp_gt_i32_e32 vcc, 2, v244
	v_cmp_gt_i32_e64 s[22:23], 3, v244
	s_nop 0
	v_cndmask_b32_e32 v80, v80, v199, vcc
	v_cndmask_b32_e64 v81, v81, v199, s[22:23]

.Lsb_wd_74:
	s_bfe_u32 s22, s17, 0x40000
	s_cmp_eq_u32 s22, 0
	s_cbranch_scc1 .Lsb_sg_75
	s_lshr_b32 s22, s17, 0
	v_lshrrev_b32_e64 v203, v165, s22
	v_and_b32_e32 v203, 1, v203
	v_cmp_eq_u32_e64 s[10:11], 1, v203
	s_setprio 1
	v_mfma_f32_16x16x32_fp8_fp8 v[66:69], v[212:213], v[144:145], 0
	v_mfma_f32_16x16x32_fp8_fp8 v[70:73], v[216:217], v[144:145], 0
	v_mfma_f32_16x16x32_fp8_fp8 v[74:77], v[220:221], v[144:145], 0
	v_mfma_f32_16x16x32_fp8_fp8 v[78:81], v[224:225], v[144:145], 0
	v_mfma_f32_16x16x32_fp8_fp8 v[66:69], v[214:215], v[146:147], v[66:69]
	v_mfma_f32_16x16x32_fp8_fp8 v[70:73], v[218:219], v[146:147], v[70:73]
	v_mfma_f32_16x16x32_fp8_fp8 v[74:77], v[222:223], v[146:147], v[74:77]
	v_mfma_f32_16x16x32_fp8_fp8 v[78:81], v[226:227], v[146:147], v[78:81]
	s_setprio 0
	v_cndmask_b32_e64 v204, v200, v158, s[10:11]
	s_cmp_eq_u32 s14, s48
	s_nop 1
	s_cbranch_scc1 .Lsb_dg_76

.Lsb_pv_79:
	v_add_f32_e32 v159, v159, v244
	s_setprio 1
	v_mfma_f32_16x16x32_fp8_fp8 v[102:105], v[228:229], v[154:155], v[102:105]
	v_mfma_f32_16x16x32_fp8_fp8 v[106:109], v[232:233], v[154:155], v[106:109]
	v_mfma_f32_16x16x32_fp8_fp8 v[110:113], v[236:237], v[154:155], v[110:113]
	v_mfma_f32_16x16x32_fp8_fp8 v[114:117], v[240:241], v[154:155], v[114:117]
	v_mfma_f32_16x16x32_fp8_fp8 v[102:105], v[230:231], v[156:157], v[102:105]
	v_mfma_f32_16x16x32_fp8_fp8 v[106:109], v[234:235], v[156:157], v[106:109]
	v_mfma_f32_16x16x32_fp8_fp8 v[110:113], v[238:239], v[156:157], v[110:113]
	v_mfma_f32_16x16x32_fp8_fp8 v[114:117], v[242:243], v[156:157], v[114:117]
	s_setprio 0
	s_branch .Lsb_ce_82

.Lsb_sl_78:
	s_setprio 1
	v_mfma_f32_16x16x32_fp8_fp8 v[66:69], v[212:213], v[144:145], 0
	v_mfma_f32_16x16x32_fp8_fp8 v[70:73], v[216:217], v[144:145], 0
	v_mfma_f32_16x16x32_fp8_fp8 v[74:77], v[220:221], v[144:145], 0
	v_mfma_f32_16x16x32_fp8_fp8 v[78:81], v[224:225], v[144:145], 0
	v_mfma_f32_16x16x32_fp8_fp8 v[66:69], v[214:215], v[146:147], v[66:69]
	v_mfma_f32_16x16x32_fp8_fp8 v[70:73], v[218:219], v[146:147], v[70:73]
	v_mfma_f32_16x16x32_fp8_fp8 v[74:77], v[222:223], v[146:147], v[74:77]
	v_mfma_f32_16x16x32_fp8_fp8 v[78:81], v[226:227], v[146:147], v[78:81]
	s_setprio 0
	s_cmp_lg_u32 s14, s48
	s_nop 7
	s_cbranch_scc1 .Lsb_sn_81
	v_sub_u32_e32 v244, v206, v187
	v_cmp_gt_i32_e32 vcc, 0, v244
	v_cmp_gt_i32_e64 s[22:23], 1, v244
	s_nop 0
	v_cndmask_b32_e32 v66, v66, v199, vcc
	v_cndmask_b32_e64 v67, v67, v199, s[22:23]
	v_cmp_gt_i32_e32 vcc, 2, v244
	v_cmp_gt_i32_e64 s[22:23], 3, v244
	s_nop 0
	v_cndmask_b32_e32 v68, v68, v199, vcc
	v_cndmask_b32_e64 v69, v69, v199, s[22:23]
	v_sub_u32_e32 v244, v206, v187
	v_subrev_u32_e32 v244, 16, v244
	v_cmp_gt_i32_e32 vcc, 0, v244
	v_cmp_gt_i32_e64 s[22:23], 1, v244
	s_nop 0
	v_cndmask_b32_e32 v70, v70, v199, vcc
	v_cndmask_b32_e64 v71, v71, v199, s[22:23]
	v_cmp_gt_i32_e32 vcc, 2, v244
	v_cmp_gt_i32_e64 s[22:23], 3, v244
	s_nop 0
	v_cndmask_b32_e32 v72, v72, v199, vcc
	v_cndmask_b32_e64 v73, v73, v199, s[22:23]
	v_sub_u32_e32 v244, v206, v187
	v_subrev_u32_e32 v244, 32, v244
	v_cmp_gt_i32_e32 vcc, 0, v244
	v_cmp_gt_i32_e64 s[22:23], 1, v244
	s_nop 0
	v_cndmask_b32_e32 v74, v74, v199, vcc
	v_cndmask_b32_e64 v75, v75, v199, s[22:23]
	v_cmp_gt_i32_e32 vcc, 2, v244
	v_cmp_gt_i32_e64 s[22:23], 3, v244
	s_nop 0
	v_cndmask_b32_e32 v76, v76, v199, vcc
	v_cndmask_b32_e64 v77, v77, v199, s[22:23]
	v_sub_u32_e32 v244, v206, v187
	v_subrev_u32_e32 v244, 48, v244
	v_cmp_gt_i32_e32 vcc, 0, v244
	v_cmp_gt_i32_e64 s[22:23], 1, v244
	s_nop 0
	v_cndmask_b32_e32 v78, v78, v199, vcc
	v_cndmask_b32_e64 v79, v79, v199, s[22:23]
	v_cmp_gt_i32_e32 vcc, 2, v244
	v_cmp_gt_i32_e64 s[22:23], 3, v244
	s_nop 0
	v_cndmask_b32_e32 v80, v80, v199, vcc
	v_cndmask_b32_e64 v81, v81, v199, s[22:23]

.Lsb_ce_82:
.Lsb_sg_75:
	s_bfe_u32 s22, s17, 0x40004
	s_cmp_eq_u32 s22, 0
	s_cbranch_scc1 .Lsb_sg_83
	s_lshr_b32 s22, s17, 4
	v_lshrrev_b32_e64 v203, v165, s22
	v_and_b32_e32 v203, 1, v203
	v_cmp_eq_u32_e64 s[10:11], 1, v203
	s_setprio 1
	v_mfma_f32_16x16x32_fp8_fp8 v[66:69], v[212:213], v[150:151], 0
	v_mfma_f32_16x16x32_fp8_fp8 v[70:73], v[216:217], v[150:151], 0
	v_mfma_f32_16x16x32_fp8_fp8 v[74:77], v[220:221], v[150:151], 0
	v_mfma_f32_16x16x32_fp8_fp8 v[78:81], v[224:225], v[150:151], 0
	v_mfma_f32_16x16x32_fp8_fp8 v[66:69], v[214:215], v[152:153], v[66:69]
	v_mfma_f32_16x16x32_fp8_fp8 v[70:73], v[218:219], v[152:153], v[70:73]
	v_mfma_f32_16x16x32_fp8_fp8 v[74:77], v[222:223], v[152:153], v[74:77]
	v_mfma_f32_16x16x32_fp8_fp8 v[78:81], v[226:227], v[152:153], v[78:81]
	s_setprio 0
	v_cndmask_b32_e64 v204, v200, v162, s[10:11]
	s_cmp_eq_u32 s14, s48
	s_nop 1
	s_cbranch_scc1 .Lsb_dg_84

.Lsb_pv_87:
	v_add_f32_e32 v163, v163, v244
	s_setprio 1
	v_mfma_f32_16x16x32_fp8_fp8 v[118:121], v[228:229], v[154:155], v[118:121]
	v_mfma_f32_16x16x32_fp8_fp8 v[122:125], v[232:233], v[154:155], v[122:125]
	v_mfma_f32_16x16x32_fp8_fp8 v[136:139], v[236:237], v[154:155], v[136:139]
	v_mfma_f32_16x16x32_fp8_fp8 v[140:143], v[240:241], v[154:155], v[140:143]
	v_mfma_f32_16x16x32_fp8_fp8 v[118:121], v[230:231], v[156:157], v[118:121]
	v_mfma_f32_16x16x32_fp8_fp8 v[122:125], v[234:235], v[156:157], v[122:125]
	v_mfma_f32_16x16x32_fp8_fp8 v[136:139], v[238:239], v[156:157], v[136:139]
	v_mfma_f32_16x16x32_fp8_fp8 v[140:143], v[242:243], v[156:157], v[140:143]
	s_setprio 0
	s_branch .Lsb_ce_90

.Lsb_sl_86:
	s_setprio 1
	v_mfma_f32_16x16x32_fp8_fp8 v[66:69], v[212:213], v[150:151], 0
	v_mfma_f32_16x16x32_fp8_fp8 v[70:73], v[216:217], v[150:151], 0
	v_mfma_f32_16x16x32_fp8_fp8 v[74:77], v[220:221], v[150:151], 0
	v_mfma_f32_16x16x32_fp8_fp8 v[78:81], v[224:225], v[150:151], 0
	v_mfma_f32_16x16x32_fp8_fp8 v[66:69], v[214:215], v[152:153], v[66:69]
	v_mfma_f32_16x16x32_fp8_fp8 v[70:73], v[218:219], v[152:153], v[70:73]
	v_mfma_f32_16x16x32_fp8_fp8 v[74:77], v[222:223], v[152:153], v[74:77]
	v_mfma_f32_16x16x32_fp8_fp8 v[78:81], v[226:227], v[152:153], v[78:81]
	s_setprio 0
	s_cmp_lg_u32 s14, s48
	s_nop 7
	s_cbranch_scc1 .Lsb_sn_89
	v_sub_u32_e32 v244, v206, v187
	v_subrev_u32_e32 v244, -4, v244
	v_cmp_gt_i32_e32 vcc, 0, v244
	v_cmp_gt_i32_e64 s[22:23], 1, v244
	s_nop 0
	v_cndmask_b32_e32 v66, v66, v199, vcc
	v_cndmask_b32_e64 v67, v67, v199, s[22:23]
	v_cmp_gt_i32_e32 vcc, 2, v244
	v_cmp_gt_i32_e64 s[22:23], 3, v244
	s_nop 0
	v_cndmask_b32_e32 v68, v68, v199, vcc
	v_cndmask_b32_e64 v69, v69, v199, s[22:23]
	v_sub_u32_e32 v244, v206, v187
	v_subrev_u32_e32 v244, 12, v244
	v_cmp_gt_i32_e32 vcc, 0, v244
	v_cmp_gt_i32_e64 s[22:23], 1, v244
	s_nop 0
	v_cndmask_b32_e32 v70, v70, v199, vcc
	v_cndmask_b32_e64 v71, v71, v199, s[22:23]
	v_cmp_gt_i32_e32 vcc, 2, v244
	v_cmp_gt_i32_e64 s[22:23], 3, v244
	s_nop 0
	v_cndmask_b32_e32 v72, v72, v199, vcc
	v_cndmask_b32_e64 v73, v73, v199, s[22:23]
	v_sub_u32_e32 v244, v206, v187
	v_subrev_u32_e32 v244, 28, v244
	v_cmp_gt_i32_e32 vcc, 0, v244
	v_cmp_gt_i32_e64 s[22:23], 1, v244
	s_nop 0
	v_cndmask_b32_e32 v74, v74, v199, vcc
	v_cndmask_b32_e64 v75, v75, v199, s[22:23]
	v_cmp_gt_i32_e32 vcc, 2, v244
	v_cmp_gt_i32_e64 s[22:23], 3, v244
	s_nop 0
	v_cndmask_b32_e32 v76, v76, v199, vcc
	v_cndmask_b32_e64 v77, v77, v199, s[22:23]
	v_sub_u32_e32 v244, v206, v187
	v_subrev_u32_e32 v244, 44, v244
	v_cmp_gt_i32_e32 vcc, 0, v244
	v_cmp_gt_i32_e64 s[22:23], 1, v244
	s_nop 0
	v_cndmask_b32_e32 v78, v78, v199, vcc
	v_cndmask_b32_e64 v79, v79, v199, s[22:23]
	v_cmp_gt_i32_e32 vcc, 2, v244
	v_cmp_gt_i32_e64 s[22:23], 3, v244
	s_nop 0
	v_cndmask_b32_e32 v80, v80, v199, vcc
	v_cndmask_b32_e64 v81, v81, v199, s[22:23]

.Lsb_ce_90:
.Lsb_sg_83:
	s_mov_b32 s14, s15
	s_mov_b32 s15, s16
	s_mov_b32 s17, s18
	s_mov_b32 s18, s19
	s_mov_b32 s24, s25
	s_branch .Lsb_step0

.LBB0_4169:
	s_nop 3
	v_max3_f32 v1, v35, v51, v36
	v_max3_f32 v108, v52, v37, v53
	v_max3_f32 v109, v50, v34, v38
	v_max3_f32 v110, v54, v39, v55
	v_max3_f32 v1, v1, v40, v56
	v_max3_f32 v108, v108, v41, v57
	v_max3_f32 v109, v109, v42, v58
	v_max3_f32 v110, v110, v43, v59
	v_max3_f32 v1, v1, v44, v60
	v_max3_f32 v108, v108, v45, v61
	v_max3_f32 v109, v109, v46, v62
	v_max3_f32 v110, v110, v47, v63
	v_max3_f32 v1, v1, v48, v64
	v_max3_f32 v108, v108, v49, v65
	v_max3_f32 v1, v1, v108, v109
	v_max_f32_e32 v1, v1, v110
	ds_bpermute_b32 v108, v179, v1
	s_waitcnt lgkmcnt(0)
	v_max3_f32 v1, v107, v1, v108
	v_sub_f32_e32 v107, v107, v1
	v_exp_f32_e32 v107, v107
	s_nop 0
	v_cmp_eq_f32_e32 vcc, 1.0, v107
	s_cmp_eq_u64 vcc, exec
	s_cbranch_scc1 .LBB0_4173
	s_and_saveexec_b64 s[10:11], s[8:9]
	ds_write_b32 v104, v107 offset:32768
	s_or_b64 exec, exec, s[10:11]
	ds_read_b128 v[108:111], v105 offset:32864
	ds_read_b128 v[112:115], v105 offset:32832
	ds_read_b128 v[116:119], v105 offset:32800
	ds_read_b128 v[120:123], v105 offset:32768
	s_waitcnt lgkmcnt(3)
	v_pk_mul_f32 v[30:31], v[30:31], v[108:109]
	s_waitcnt lgkmcnt(2)
	v_pk_mul_f32 v[26:27], v[26:27], v[112:113]
	s_waitcnt lgkmcnt(1)
	v_pk_mul_f32 v[22:23], v[22:23], v[116:117]
	s_waitcnt lgkmcnt(0)
	v_pk_mul_f32 v[18:19], v[18:19], v[120:121]
	v_pk_mul_f32 v[14:15], v[14:15], v[108:109]
	v_pk_mul_f32 v[10:11], v[10:11], v[112:113]
	v_pk_mul_f32 v[6:7], v[6:7], v[116:117]
	v_pk_mul_f32 v[32:33], v[32:33], v[110:111]
	v_pk_mul_f32 v[28:29], v[28:29], v[114:115]
	v_pk_mul_f32 v[24:25], v[24:25], v[118:119]
	v_pk_mul_f32 v[20:21], v[20:21], v[122:123]
	v_pk_mul_f32 v[16:17], v[16:17], v[110:111]
	v_pk_mul_f32 v[12:13], v[12:13], v[114:115]
	v_pk_mul_f32 v[8:9], v[8:9], v[118:119]
	v_pk_mul_f32 v[4:5], v[4:5], v[122:123]
	v_pk_mul_f32 v[2:3], v[2:3], v[120:121]
